# G2 stagger: every non-sample group delayed (1..4 steps of s_sleep 45), sample workgroups alone in their epilogue
# baseline (speedup 1.0000x reference)
.LBB0_509:
	s_or_b64 exec, exec, s[6:7]
	s_lshl_b64 s[6:7], s[28:29], 22
	v_readlane_b32 s16, v254, 4
	s_add_u32 s19, s16, s6
	v_readlane_b32 s6, v254, 5
	s_addc_u32 s20, s6, s7
	v_readlane_b32 s6, v254, 6
	s_waitcnt lgkmcnt(0)
	s_barrier
	s_cmpk_lt_u32 s2, 0x40
	s_cbranch_scc1 .Lg2stag_done
	s_bfe_u32 s98, s2, 0x20003
	s_add_i32 s98, s98, 1
	s_cmp_eq_u32 s98, 0
	s_cbranch_scc1 .Lg2stag_done
.Lg2stag_loop:
	s_sleep 45
	s_sub_u32 s98, s98, 1
	s_cmp_lg_u32 s98, 0
	s_cbranch_scc1 .Lg2stag_loop
